# gating MFMA pass rewrite + retire next-head prefetch loads at pass end (counted waits independent of store count)
# speedup vs baseline: 1.0039x; 1.0011x over previous
.LBB0_522:
	s_waitcnt vmcnt(9)
	v_cndmask_b32_e64 v80, v80, 0, s[2:3]
	v_bfe_u32 v138, v80, 16, 1
	v_cndmask_b32_e64 v81, 0, v81, s[4:5]
	v_add3_u32 v80, v80, v138, s85
	v_bfe_u32 v138, v81, 16, 1
	v_lshrrev_b32_e32 v80, 16, v80
	v_add3_u32 v81, v81, v138, s85
	v_and_or_b32 v80, v81, s84, v80
	v_cndmask_b32_e64 v81, v82, 0, s[6:7]
	v_bfe_u32 v82, v81, 16, 1
	v_add3_u32 v81, v81, v82, s85
	v_cndmask_b32_e64 v82, v83, 0, s[8:9]
	v_bfe_u32 v83, v82, 16, 1
	v_add_u32_e32 v141, s89, v129
	v_lshrrev_b32_e32 v81, 16, v81
	v_add3_u32 v82, v82, v83, s85
	v_cndmask_b32_e64 v72, v72, 0, s[10:11]
	v_add_u32_e32 v138, v141, v130
	v_and_or_b32 v81, v82, s84, v81
	v_bfe_u32 v82, v72, 16, 1
	v_cndmask_b32_e64 v73, v73, 0, s[12:13]
	v_add3_u32 v72, v72, v82, s85
	v_bfe_u32 v82, v73, 16, 1
	v_lshrrev_b32_e32 v72, 16, v72
	v_add3_u32 v73, v73, v82, s85
	v_and_or_b32 v82, v73, s84, v72
	v_cndmask_b32_e64 v72, v74, 0, s[14:15]
	v_bfe_u32 v73, v72, 16, 1
	v_add3_u32 v72, v72, v73, s85
	v_cndmask_b32_e64 v73, v75, 0, s[16:17]
	v_bfe_u32 v74, v73, 16, 1
	v_lshrrev_b32_e32 v72, 16, v72
	v_add3_u32 v73, v73, v74, s85
	v_and_or_b32 v83, v73, s84, v72
	v_add_u32_e32 v150, v141, v131
	v_add_u32_e32 v151, v141, v132
	v_add_u32_e32 v152, v141, v133
	v_add_u32_e32 v153, v141, v134
	v_add_u32_e32 v154, v141, v128
	v_add_u32_e32 v155, v141, v135
	v_add_u32_e32 v156, v141, v136
	ds_read_b128 v[160:163], v138
	ds_read_b128 v[164:167], v138 offset:64
	ds_read_b128 v[168:171], v138 offset:128
	ds_read_b128 v[172:175], v138 offset:192
	ds_read_b128 v[176:179], v150 offset:4352
	ds_read_b128 v[180:183], v150 offset:4416
	ds_read_b128 v[184:187], v150 offset:4480
	ds_read_b128 v[188:191], v150 offset:4544
	ds_read_b128 v[192:195], v151 offset:8704
	ds_read_b128 v[196:199], v152 offset:8704
	ds_read_b128 v[200:203], v151 offset:8832
	ds_read_b128 v[204:207], v153 offset:8704
	ds_read_b128 v[208:211], v154 offset:13056
	ds_read_b128 v[212:215], v155 offset:13056
	ds_read_b128 v[216:219], v154 offset:13184
	ds_read_b128 v[220:223], v156 offset:13056
	v_mbcnt_lo_u32_b32 v148, -1, 0
	v_mbcnt_hi_u32_b32 v148, -1, v148
	v_lshrrev_b32_e32 v148, 4, v148
	v_and_b32_e32 v148, 1, v148
	v_mul_u32_u24_e32 v148, 24, v148
	v_mov_b32_e32 v149, 0
	v_lshl_add_u64 v[158:159], v[96:97], 0, s[0:1]
	v_lshl_add_u64 v[158:159], v[158:159], 0, v[148:149]
	s_waitcnt lgkmcnt(8)
	v_mfma_f32_16x16x32_bf16 v[224:227], v[160:163], v[80:83], 0
	v_mfma_f32_16x16x32_bf16 v[228:231], v[176:179], v[80:83], 0
	v_mfma_f32_16x16x32_bf16 v[224:227], v[164:167], v[76:79], v[224:227]
	v_mfma_f32_16x16x32_bf16 v[228:231], v[180:183], v[76:79], v[228:231]
	v_mfma_f32_16x16x32_bf16 v[224:227], v[168:171], v[84:87], v[224:227]
	v_mfma_f32_16x16x32_bf16 v[228:231], v[184:187], v[84:87], v[228:231]
	v_mfma_f32_16x16x32_bf16 v[224:227], v[172:175], v[88:91], v[224:227]
	v_mfma_f32_16x16x32_bf16 v[228:231], v[188:191], v[88:91], v[228:231]
	ds_read_b128 v[160:163], v138 offset:17408
	ds_read_b128 v[164:167], v138 offset:17472
	ds_read_b128 v[168:171], v138 offset:17536
	ds_read_b128 v[172:175], v138 offset:17600
	ds_read_b128 v[176:179], v150 offset:21760
	ds_read_b128 v[180:183], v150 offset:21824
	ds_read_b128 v[184:187], v150 offset:21888
	ds_read_b128 v[188:191], v150 offset:21952
	s_waitcnt lgkmcnt(8)
	v_mfma_f32_16x16x32_bf16 v[232:235], v[192:195], v[80:83], 0
	v_mfma_f32_16x16x32_bf16 v[236:239], v[208:211], v[80:83], 0
	v_mfma_f32_16x16x32_bf16 v[232:235], v[196:199], v[76:79], v[232:235]
	v_mfma_f32_16x16x32_bf16 v[236:239], v[212:215], v[76:79], v[236:239]
	v_mfma_f32_16x16x32_bf16 v[232:235], v[200:203], v[84:87], v[232:235]
	v_mfma_f32_16x16x32_bf16 v[236:239], v[216:219], v[84:87], v[236:239]
	v_mfma_f32_16x16x32_bf16 v[232:235], v[204:207], v[88:91], v[232:235]
	v_mfma_f32_16x16x32_bf16 v[236:239], v[220:223], v[88:91], v[236:239]
	ds_read_b128 v[192:195], v151 offset:26112
	ds_read_b128 v[196:199], v152 offset:26112
	ds_read_b128 v[200:203], v151 offset:26240
	ds_read_b128 v[204:207], v153 offset:26112
	ds_read_b128 v[208:211], v154 offset:30464
	ds_read_b128 v[212:215], v155 offset:30464
	ds_read_b128 v[216:219], v154 offset:30592
	ds_read_b128 v[220:223], v156 offset:30464
	s_waitcnt vmcnt(6)
	v_lshlrev_b32_e32 v248, 16, v122
	v_add_f32_e32 v249, v137, v224
	v_mul_f32_e32 v249, v249, v248
	v_and_b32_e32 v248, 0xffff0000, v122
	v_add_f32_e32 v250, v137, v225
	v_mul_f32_e32 v250, v250, v248
	v_cvt_pk_bf16_f32 v240, v249, v250
	v_lshlrev_b32_e32 v248, 16, v123
	v_add_f32_e32 v249, v137, v226
	v_mul_f32_e32 v249, v249, v248
	v_and_b32_e32 v248, 0xffff0000, v123
	v_add_f32_e32 v250, v137, v227
	v_mul_f32_e32 v250, v250, v248
	v_cvt_pk_bf16_f32 v241, v249, v250
	v_lshlrev_b32_e32 v248, 16, v120
	v_add_f32_e32 v249, v137, v228
	v_mul_f32_e32 v249, v249, v248
	v_and_b32_e32 v248, 0xffff0000, v120
	v_add_f32_e32 v250, v137, v229
	v_mul_f32_e32 v250, v250, v248
	v_cvt_pk_bf16_f32 v242, v249, v250
	v_lshlrev_b32_e32 v248, 16, v121
	v_add_f32_e32 v249, v137, v230
	v_mul_f32_e32 v249, v249, v248
	v_and_b32_e32 v248, 0xffff0000, v121
	v_add_f32_e32 v250, v137, v231
	v_mul_f32_e32 v250, v250, v248
	v_cvt_pk_bf16_f32 v243, v249, v250
	s_nop 1
	v_permlane16_swap_b32_e32 v240, v242
	v_permlane16_swap_b32_e32 v241, v243
	global_store_dwordx4 v[158:159], v[240:243], off offset:-128
	s_waitcnt lgkmcnt(8)
	v_mfma_f32_16x16x32_bf16 v[224:227], v[160:163], v[80:83], 0
	v_mfma_f32_16x16x32_bf16 v[228:231], v[176:179], v[80:83], 0
	v_mfma_f32_16x16x32_bf16 v[224:227], v[164:167], v[76:79], v[224:227]
	v_mfma_f32_16x16x32_bf16 v[228:231], v[180:183], v[76:79], v[228:231]
	v_mfma_f32_16x16x32_bf16 v[224:227], v[168:171], v[84:87], v[224:227]
	v_mfma_f32_16x16x32_bf16 v[228:231], v[184:187], v[84:87], v[228:231]
	v_mfma_f32_16x16x32_bf16 v[224:227], v[172:175], v[88:91], v[224:227]
	v_mfma_f32_16x16x32_bf16 v[228:231], v[188:191], v[88:91], v[228:231]
	s_waitcnt vmcnt(5)
	v_lshlrev_b32_e32 v248, 16, v118
	v_add_f32_e32 v249, v137, v232
	v_mul_f32_e32 v249, v249, v248
	v_and_b32_e32 v248, 0xffff0000, v118
	v_add_f32_e32 v250, v137, v233
	v_mul_f32_e32 v250, v250, v248
	v_cvt_pk_bf16_f32 v244, v249, v250
	v_lshlrev_b32_e32 v248, 16, v119
	v_add_f32_e32 v249, v137, v234
	v_mul_f32_e32 v249, v249, v248
	v_and_b32_e32 v248, 0xffff0000, v119
	v_add_f32_e32 v250, v137, v235
	v_mul_f32_e32 v250, v250, v248
	v_cvt_pk_bf16_f32 v245, v249, v250
	v_lshlrev_b32_e32 v248, 16, v116
	v_add_f32_e32 v249, v137, v236
	v_mul_f32_e32 v249, v249, v248
	v_and_b32_e32 v248, 0xffff0000, v116
	v_add_f32_e32 v250, v137, v237
	v_mul_f32_e32 v250, v250, v248
	v_cvt_pk_bf16_f32 v246, v249, v250
	v_lshlrev_b32_e32 v248, 16, v117
	v_add_f32_e32 v249, v137, v238
	v_mul_f32_e32 v249, v249, v248
	v_and_b32_e32 v248, 0xffff0000, v117
	v_add_f32_e32 v250, v137, v239
	v_mul_f32_e32 v250, v250, v248
	v_cvt_pk_bf16_f32 v247, v249, v250
	s_nop 1
	v_permlane16_swap_b32_e32 v244, v246
	v_permlane16_swap_b32_e32 v245, v247
	global_store_dwordx4 v[158:159], v[244:247], off offset:-64
	s_waitcnt lgkmcnt(0)
	v_mfma_f32_16x16x32_bf16 v[232:235], v[192:195], v[80:83], 0
	v_mfma_f32_16x16x32_bf16 v[236:239], v[208:211], v[80:83], 0
	v_mfma_f32_16x16x32_bf16 v[232:235], v[196:199], v[76:79], v[232:235]
	v_mfma_f32_16x16x32_bf16 v[236:239], v[212:215], v[76:79], v[236:239]
	v_mfma_f32_16x16x32_bf16 v[232:235], v[200:203], v[84:87], v[232:235]
	v_mfma_f32_16x16x32_bf16 v[236:239], v[216:219], v[84:87], v[236:239]
	v_mfma_f32_16x16x32_bf16 v[232:235], v[204:207], v[88:91], v[232:235]
	v_mfma_f32_16x16x32_bf16 v[236:239], v[220:223], v[88:91], v[236:239]
	s_waitcnt vmcnt(4)
	v_lshlrev_b32_e32 v248, 16, v114
	v_add_f32_e32 v249, v137, v224
	v_mul_f32_e32 v249, v249, v248
	v_and_b32_e32 v248, 0xffff0000, v114
	v_add_f32_e32 v250, v137, v225
	v_mul_f32_e32 v250, v250, v248
	v_cvt_pk_bf16_f32 v240, v249, v250
	v_lshlrev_b32_e32 v248, 16, v115
	v_add_f32_e32 v249, v137, v226
	v_mul_f32_e32 v249, v249, v248
	v_and_b32_e32 v248, 0xffff0000, v115
	v_add_f32_e32 v250, v137, v227
	v_mul_f32_e32 v250, v250, v248
	v_cvt_pk_bf16_f32 v241, v249, v250
	v_lshlrev_b32_e32 v248, 16, v112
	v_add_f32_e32 v249, v137, v228
	v_mul_f32_e32 v249, v249, v248
	v_and_b32_e32 v248, 0xffff0000, v112
	v_add_f32_e32 v250, v137, v229
	v_mul_f32_e32 v250, v250, v248
	v_cvt_pk_bf16_f32 v242, v249, v250
	v_lshlrev_b32_e32 v248, 16, v113
	v_add_f32_e32 v249, v137, v230
	v_mul_f32_e32 v249, v249, v248
	v_and_b32_e32 v248, 0xffff0000, v113
	v_add_f32_e32 v250, v137, v231
	v_mul_f32_e32 v250, v250, v248
	v_cvt_pk_bf16_f32 v243, v249, v250
	s_nop 1
	v_permlane16_swap_b32_e32 v240, v242
	v_permlane16_swap_b32_e32 v241, v243
	global_store_dwordx4 v[158:159], v[240:243], off offset:0
	s_nop 7
	s_nop 7
	s_waitcnt vmcnt(3)
	v_lshlrev_b32_e32 v248, 16, v110
	v_add_f32_e32 v249, v137, v232
	v_mul_f32_e32 v249, v249, v248
	v_and_b32_e32 v248, 0xffff0000, v110
	v_add_f32_e32 v250, v137, v233
	v_mul_f32_e32 v250, v250, v248
	v_cvt_pk_bf16_f32 v244, v249, v250
	v_lshlrev_b32_e32 v248, 16, v111
	v_add_f32_e32 v249, v137, v234
	v_mul_f32_e32 v249, v249, v248
	v_and_b32_e32 v248, 0xffff0000, v111
	v_add_f32_e32 v250, v137, v235
	v_mul_f32_e32 v250, v250, v248
	v_cvt_pk_bf16_f32 v245, v249, v250
	v_lshlrev_b32_e32 v248, 16, v108
	v_add_f32_e32 v249, v137, v236
	v_mul_f32_e32 v249, v249, v248
	v_and_b32_e32 v248, 0xffff0000, v108
	v_add_f32_e32 v250, v137, v237
	v_mul_f32_e32 v250, v250, v248
	v_cvt_pk_bf16_f32 v246, v249, v250
	v_lshlrev_b32_e32 v248, 16, v109
	v_add_f32_e32 v249, v137, v238
	v_mul_f32_e32 v249, v249, v248
	v_and_b32_e32 v248, 0xffff0000, v109
	v_add_f32_e32 v250, v137, v239
	v_mul_f32_e32 v250, v250, v248
	v_cvt_pk_bf16_f32 v247, v249, v250
	s_nop 1
	v_permlane16_swap_b32_e32 v244, v246
	v_permlane16_swap_b32_e32 v245, v247
	global_store_dwordx4 v[158:159], v[244:247], off offset:64
	s_waitcnt vmcnt(4)
	s_branch .LBB0_506
